# combination + F1 epilogue zeroing of the conv history registers out of line at all 8 sites
# speedup vs baseline: 1.0072x; 1.0014x over previous
; #define PG8_LAS __attribute__((address_space(3)))
;     __device__ __forceinline__ void operator()(f32x4 (&acc)[2][2][4][2], const Unit& u, int p, int wr, int wc, int fr, int fq) const {
;     ...
;                     f32x4 h62 = (f32x4){0.f, 0.f, 0.f, 0.f}, h63 = h62;
;                     if (g > 0) { h62 = *(const PG8_LAS f32x4*)(X + (((g - 1) * 2 + 0) * 256) + bj * 128 + tcol + 4 * n); h63 = *(const PG8_LAS f32x4*)(X + (((g - 1) * 2 + 1) * 256) + bj * 128 + tcol + 4 * n); }
.Lzd_1:
	v_mov_b32_e32 v94, 0
	v_mov_b32_e32 v95, 0
	v_mov_b32_e32 v96, 0
	v_mov_b32_e32 v97, 0
	v_mov_b32_e32 v142, 0
	v_mov_b32_e32 v143, 0
	v_mov_b32_e32 v144, 0
	v_mov_b32_e32 v145, 0
	s_branch .LBB0_1339

; #define PG8_LAS __attribute__((address_space(3)))
;     __device__ __forceinline__ void operator()(f32x4 (&acc)[2][2][4][2], const Unit& u, int p, int wr, int wc, int fr, int fq) const {
;     ...
;                     f32x4 h62 = (f32x4){0.f, 0.f, 0.f, 0.f}, h63 = h62;
;                     if (g > 0) { h62 = *(const PG8_LAS f32x4*)(X + (((g - 1) * 2 + 0) * 256) + bj * 128 + tcol + 4 * n); h63 = *(const PG8_LAS f32x4*)(X + (((g - 1) * 2 + 1) * 256) + bj * 128 + tcol + 4 * n); }
.Lzd_3:
	v_mov_b32_e32 v158, 0
	v_mov_b32_e32 v159, 0
	v_mov_b32_e32 v160, 0
	v_mov_b32_e32 v161, 0
	v_mov_b32_e32 v170, 0
	v_mov_b32_e32 v171, 0
	v_mov_b32_e32 v172, 0
	v_mov_b32_e32 v173, 0
	s_branch .LBB0_1343

; #define PG8_LAS __attribute__((address_space(3)))
;     __device__ __forceinline__ void operator()(f32x4 (&acc)[2][2][4][2], const Unit& u, int p, int wr, int wc, int fr, int fq) const {
;     ...
;                     f32x4 h62 = (f32x4){0.f, 0.f, 0.f, 0.f}, h63 = h62;
;                     if (g > 0) { h62 = *(const PG8_LAS f32x4*)(X + (((g - 1) * 2 + 0) * 256) + bj * 128 + tcol + 4 * n); h63 = *(const PG8_LAS f32x4*)(X + (((g - 1) * 2 + 1) * 256) + bj * 128 + tcol + 4 * n); }
.Lzd_5:
	v_mov_b32_e32 v86, 0
	v_mov_b32_e32 v87, 0
	v_mov_b32_e32 v88, 0
	v_mov_b32_e32 v89, 0
	v_mov_b32_e32 v102, 0
	v_mov_b32_e32 v103, 0
	v_mov_b32_e32 v104, 0
	v_mov_b32_e32 v105, 0
	s_branch .LBB0_1347

; #define PG8_LAS __attribute__((address_space(3)))
;     __device__ __forceinline__ void operator()(f32x4 (&acc)[2][2][4][2], const Unit& u, int p, int wr, int wc, int fr, int fq) const {
;     ...
;                     f32x4 h62 = (f32x4){0.f, 0.f, 0.f, 0.f}, h63 = h62;
;                     if (g > 0) { h62 = *(const PG8_LAS f32x4*)(X + (((g - 1) * 2 + 0) * 256) + bj * 128 + tcol + 4 * n); h63 = *(const PG8_LAS f32x4*)(X + (((g - 1) * 2 + 1) * 256) + bj * 128 + tcol + 4 * n); }
.Lzd_7:
	v_mov_b32_e32 v58, 0
	v_mov_b32_e32 v59, 0
	v_mov_b32_e32 v60, 0
	v_mov_b32_e32 v61, 0
	v_mov_b32_e32 v90, 0
	v_mov_b32_e32 v91, 0
	v_mov_b32_e32 v92, 0
	v_mov_b32_e32 v93, 0
	s_branch .LBB0_1351

; #define PG8_LAS __attribute__((address_space(3)))
; template <int SH> __device__ __forceinline__ float dpp_shr_fill(float fill, float cur) { return i2f(__builtin_amdgcn_update_dpp(f2i(fill), f2i(cur), 0x110 + SH, 0xf, 0xf, false)); }
;     __device__ __forceinline__ void operator()(f32x4 (&acc)[2][2][4][2], const Unit& u, int p, int wr, int wc, int fr, int fq) const {
;     ...
;         asm volatile("s_waitcnt lgkmcnt(0)" ::: "memory"); __builtin_amdgcn_s_barrier(); asm volatile("" ::: "memory");
;         const PG8_LAS float* Tw = TW + p * 1024 + tcol;
;         const int row0 = u.pm * BM + wr * 64 + 4 * fr;
; #pragma unroll
;         for (int ai = 0; ai < 2; ++ai) { const int g = ai * 2 + wr;
; #pragma unroll
;             for (int bj = 0; bj < 2; ++bj)
; #pragma unroll
;                 for (int n = 0; n < 2; ++n) {
;                     const f32x4 w0 = *(const PG8_LAS f32x4*)(Tw + bj * 128 + 4 * n), w1 = *(const PG8_LAS f32x4*)(Tw + 256 + bj * 128 + 4 * n), w2 = *(const PG8_LAS f32x4*)(Tw + 512 + bj * 128 + 4 * n), bb = *(const PG8_LAS f32x4*)(Tw + 768 + bj * 128 + 4 * n);
;                     f32x4 h62 = (f32x4){0.f, 0.f, 0.f, 0.f}, h63 = h62;
;                     if (g > 0) { h62 = *(const PG8_LAS f32x4*)(X + (((g - 1) * 2 + 0) * 256) + bj * 128 + tcol + 4 * n); h63 = *(const PG8_LAS f32x4*)(X + (((g - 1) * 2 + 1) * 256) + bj * 128 + tcol + 4 * n); }
;                     const f32x4 x0 = acc[ai][bj][0][n], x1 = acc[ai][bj][1][n], x2 = acc[ai][bj][2][n], x3 = acc[ai][bj][3][n];
;                     f32x4 s2, s3;
; #pragma unroll
;                     for (int e = 0; e < 4; ++e) { s3[e] = dpp_shr_fill<1>(h63[e], x3[e]); s2[e] = dpp_shr_fill<1>(h62[e], x2[e]); }
;                     f32x4 r0 = bb + w2 * x0 + w1 * s3 + w0 * s2, r1 = bb + w2 * x1 + w1 * x0 + w0 * s3, r2 = bb + w2 * x2 + w1 * x1 + w0 * x0, r3 = bb + w2 * x3 + w1 * x2 + w0 * x1;
;                     asm volatile("" : "+v"(r0), "+v"(r1), "+v"(r2), "+v"(r3));
;                     acc[ai][bj][0][n] = r0; acc[ai][bj][1][n] = r1; acc[ai][bj][2][n] = r2; acc[ai][bj][3][n] = r3;
.LBB0_1335:
	s_or_b64 exec, exec, s[12:13]
	s_lshl_b32 s0, s0, 12
	s_waitcnt lgkmcnt(0)
	s_barrier
	v_add_u32_e32 v220, s0, v209
	ds_read_b128 v[86:89], v220
	ds_read_b128 v[170:173], v220 offset:1024
	ds_read_b128 v[174:177], v220 offset:2048
	ds_read_b128 v[178:181], v220 offset:3072
	v_cndmask_b32_e64 v90, 0, 1, s[80:81]
	v_cmp_ne_u32_e64 s[12:13], 1, v90
	s_andn2_b64 vcc, exec, s[80:81]
	s_cbranch_vccnz .Lzd_0
	ds_read_b128 v[106:109], v212
	ds_read_b128 v[90:93], v211
.LBB0_1337:
	s_waitcnt lgkmcnt(0)
	s_nop 0
	v_mov_b32_dpp v90, v146 row_shr:1 row_mask:0xf bank_mask:0xf
	v_mov_b32_dpp v91, v147 row_shr:1 row_mask:0xf bank_mask:0xf
	v_mov_b32_dpp v92, v148 row_shr:1 row_mask:0xf bank_mask:0xf
	v_mov_b32_dpp v93, v149 row_shr:1 row_mask:0xf bank_mask:0xf
	v_pk_fma_f32 v[96:97], v[164:165], v[176:177], v[180:181]
	v_pk_fma_f32 v[114:115], v[162:163], v[174:175], v[178:179]
	v_mov_b32_dpp v106, v142 row_shr:1 row_mask:0xf bank_mask:0xf
	v_mov_b32_dpp v107, v143 row_shr:1 row_mask:0xf bank_mask:0xf
	v_mov_b32_dpp v108, v144 row_shr:1 row_mask:0xf bank_mask:0xf
	v_mov_b32_dpp v109, v145 row_shr:1 row_mask:0xf bank_mask:0xf
	v_pk_fma_f32 v[114:115], v[170:171], v[90:91], v[114:115]
	v_pk_fma_f32 v[96:97], v[172:173], v[92:93], v[96:97]
	v_pk_fma_f32 v[114:115], v[86:87], v[106:107], v[114:115]
	v_pk_fma_f32 v[116:117], v[88:89], v[108:109], v[96:97]
	v_pk_fma_f32 v[96:97], v[168:169], v[176:177], v[180:181]
	v_pk_fma_f32 v[106:107], v[166:167], v[174:175], v[178:179]
	v_pk_fma_f32 v[96:97], v[164:165], v[172:173], v[96:97]
	v_pk_fma_f32 v[106:107], v[162:163], v[170:171], v[106:107]
	v_pk_fma_f32 v[108:109], v[88:89], v[92:93], v[96:97]
	v_pk_fma_f32 v[106:107], v[86:87], v[90:91], v[106:107]
	v_pk_fma_f32 v[90:91], v[144:145], v[176:177], v[180:181]
	v_pk_fma_f32 v[92:93], v[142:143], v[174:175], v[178:179]
	v_pk_fma_f32 v[90:91], v[168:169], v[172:173], v[90:91]
	v_pk_fma_f32 v[96:97], v[166:167], v[170:171], v[92:93]
	v_pk_fma_f32 v[92:93], v[164:165], v[88:89], v[90:91]
	v_pk_fma_f32 v[90:91], v[162:163], v[86:87], v[96:97]
	v_pk_fma_f32 v[96:97], v[148:149], v[176:177], v[180:181]
	v_pk_fma_f32 v[146:147], v[146:147], v[174:175], v[178:179]
	v_pk_fma_f32 v[96:97], v[144:145], v[172:173], v[96:97]
	v_pk_fma_f32 v[142:143], v[142:143], v[170:171], v[146:147]
	v_pk_fma_f32 v[88:89], v[168:169], v[88:89], v[96:97]
	v_pk_fma_f32 v[86:87], v[166:167], v[86:87], v[142:143]
	s_nop 0
	ds_read_b128 v[162:165], v220 offset:16
	ds_read_b128 v[166:169], v220 offset:1040
	ds_read_b128 v[170:173], v220 offset:2064
	ds_read_b128 v[174:177], v220 offset:3088
	s_and_b64 vcc, exec, s[12:13]
	s_cbranch_vccnz .Lzd_1
	ds_read_b128 v[94:97], v214
	ds_read_b128 v[142:145], v213
.LBB0_1339:
	s_waitcnt lgkmcnt(0)
	s_nop 0
	v_mov_b32_dpp v142, v134 row_shr:1 row_mask:0xf bank_mask:0xf
	v_mov_b32_dpp v143, v135 row_shr:1 row_mask:0xf bank_mask:0xf
	v_mov_b32_dpp v144, v136 row_shr:1 row_mask:0xf bank_mask:0xf
	v_mov_b32_dpp v145, v137 row_shr:1 row_mask:0xf bank_mask:0xf
	v_pk_fma_f32 v[146:147], v[112:113], v[172:173], v[176:177]
	v_pk_fma_f32 v[148:149], v[110:111], v[170:171], v[174:175]
	v_mov_b32_dpp v94, v138 row_shr:1 row_mask:0xf bank_mask:0xf
	v_mov_b32_dpp v95, v139 row_shr:1 row_mask:0xf bank_mask:0xf
	v_mov_b32_dpp v96, v140 row_shr:1 row_mask:0xf bank_mask:0xf
	v_mov_b32_dpp v97, v141 row_shr:1 row_mask:0xf bank_mask:0xf
	v_pk_fma_f32 v[178:179], v[166:167], v[142:143], v[148:149]
	v_pk_fma_f32 v[146:147], v[168:169], v[144:145], v[146:147]
	s_nop 0
	v_pk_fma_f32 v[148:149], v[164:165], v[96:97], v[146:147]
	v_pk_fma_f32 v[146:147], v[162:163], v[94:95], v[178:179]
	v_pk_fma_f32 v[94:95], v[160:161], v[172:173], v[176:177]
	v_pk_fma_f32 v[96:97], v[158:159], v[170:171], v[174:175]
	v_pk_fma_f32 v[94:95], v[112:113], v[168:169], v[94:95]
	v_pk_fma_f32 v[96:97], v[110:111], v[166:167], v[96:97]
	v_pk_fma_f32 v[144:145], v[164:165], v[144:145], v[94:95]
	v_pk_fma_f32 v[142:143], v[162:163], v[142:143], v[96:97]
	v_pk_fma_f32 v[94:95], v[140:141], v[172:173], v[176:177]
	v_pk_fma_f32 v[96:97], v[138:139], v[170:171], v[174:175]
	v_pk_fma_f32 v[94:95], v[160:161], v[168:169], v[94:95]
	v_pk_fma_f32 v[96:97], v[158:159], v[166:167], v[96:97]
	v_pk_fma_f32 v[112:113], v[112:113], v[164:165], v[94:95]
	v_pk_fma_f32 v[110:111], v[110:111], v[162:163], v[96:97]
	v_pk_fma_f32 v[94:95], v[136:137], v[172:173], v[176:177]
	v_pk_fma_f32 v[96:97], v[134:135], v[170:171], v[174:175]
	v_pk_fma_f32 v[94:95], v[140:141], v[168:169], v[94:95]
	v_pk_fma_f32 v[134:135], v[138:139], v[166:167], v[96:97]
	v_pk_fma_f32 v[96:97], v[160:161], v[164:165], v[94:95]
	v_pk_fma_f32 v[94:95], v[158:159], v[162:163], v[134:135]
	s_nop 0
	ds_read_b128 v[166:169], v220 offset:512
	ds_read_b128 v[170:173], v220 offset:1536
	ds_read_b128 v[174:177], v220 offset:2560
	ds_read_b128 v[178:181], v220 offset:3584
	s_and_b64 vcc, exec, s[12:13]
	s_cbranch_vccnz .Lzd_2
	ds_read_b128 v[138:141], v216
	ds_read_b128 v[134:137], v215
; #define PG8_LAS __attribute__((address_space(3)))
;     __device__ __forceinline__ void operator()(f32x4 (&acc)[2][2][4][2], const Unit& u, int p, int wr, int wc, int fr, int fq) const {
;     ...
;                     const f32x4 w0 = *(const PG8_LAS f32x4*)(Tw + bj * 128 + 4 * n), w1 = *(const PG8_LAS f32x4*)(Tw + 256 + bj * 128 + 4 * n), w2 = *(const PG8_LAS f32x4*)(Tw + 512 + bj * 128 + 4 * n), bb = *(const PG8_LAS f32x4*)(Tw + 768 + bj * 128 + 4 * n);
;                     f32x4 h62 = (f32x4){0.f, 0.f, 0.f, 0.f}, h63 = h62;
;                     if (g > 0) { h62 = *(const PG8_LAS f32x4*)(X + (((g - 1) * 2 + 0) * 256) + bj * 128 + tcol + 4 * n); h63 = *(const PG8_LAS f32x4*)(X + (((g - 1) * 2 + 1) * 256) + bj * 128 + tcol + 4 * n); }
;                     const f32x4 x0 = acc[ai][bj][0][n], x1 = acc[ai][bj][1][n], x2 = acc[ai][bj][2][n], x3 = acc[ai][bj][3][n];
;                     f32x4 s2, s3;
; #pragma unroll
;                     for (int e = 0; e < 4; ++e) { s3[e] = dpp_shr_fill<1>(h63[e], x3[e]); s2[e] = dpp_shr_fill<1>(h62[e], x2[e]); }
;                     f32x4 r0 = bb + w2 * x0 + w1 * s3 + w0 * s2, r1 = bb + w2 * x1 + w1 * x0 + w0 * s3, r2 = bb + w2 * x2 + w1 * x1 + w0 * x0, r3 = bb + w2 * x3 + w1 * x2 + w0 * x1;
;                     asm volatile("" : "+v"(r0), "+v"(r1), "+v"(r2), "+v"(r3));
;                     acc[ai][bj][0][n] = r0; acc[ai][bj][1][n] = r1; acc[ai][bj][2][n] = r2; acc[ai][bj][3][n] = r3;
;                     __builtin_amdgcn_sched_barrier(0); }
; #pragma unroll
;             for (int m = 0; m < 4; ++m) { f32x4 o[2];
; #pragma unroll
;                 for (int n = 0; n < 2; ++n) { const f32x4 gt = acc[ai][0][m][n], a = gt * -1.4426950408889634f, gu = gt * acc[ai][1][m][n];
;                     f32x4 ex; ex.x = __builtin_amdgcn_exp2f(a.x); ex.y = __builtin_amdgcn_exp2f(a.y); ex.z = __builtin_amdgcn_exp2f(a.z); ex.w = __builtin_amdgcn_exp2f(a.w);
;                     const f32x4 d = ex + 1.0f; f32x4 r; r.x = __builtin_amdgcn_rcpf(d.x); r.y = __builtin_amdgcn_rcpf(d.y); r.z = __builtin_amdgcn_rcpf(d.z); r.w = __builtin_amdgcn_rcpf(d.w);
;                     o[n] = gu * r; }
;                 u32x4 w; w.x = cvt_pk_bf16(o[0][0], o[0][1]); w.y = cvt_pk_bf16(o[0][2], o[0][3]); w.z = cvt_pk_bf16(o[1][0], o[1][1]); w.w = cvt_pk_bf16(o[1][2], o[1][3]);
;                 EPI_ST16(ACT + (size_t)(row0 + ai * HALF + m) * 5504 + ch0, w); }
.LBB0_1341:
	s_waitcnt lgkmcnt(0)
	s_nop 0
	v_mov_b32_dpp v134, v126 row_shr:1 row_mask:0xf bank_mask:0xf
	v_mov_b32_dpp v135, v127 row_shr:1 row_mask:0xf bank_mask:0xf
	v_mov_b32_dpp v136, v128 row_shr:1 row_mask:0xf bank_mask:0xf
	v_mov_b32_dpp v137, v129 row_shr:1 row_mask:0xf bank_mask:0xf
	v_pk_fma_f32 v[160:161], v[156:157], v[176:177], v[180:181]
	v_pk_fma_f32 v[162:163], v[154:155], v[174:175], v[178:179]
	v_mov_b32_dpp v138, v130 row_shr:1 row_mask:0xf bank_mask:0xf
	v_mov_b32_dpp v139, v131 row_shr:1 row_mask:0xf bank_mask:0xf
	v_mov_b32_dpp v140, v132 row_shr:1 row_mask:0xf bank_mask:0xf
	v_mov_b32_dpp v141, v133 row_shr:1 row_mask:0xf bank_mask:0xf
	v_pk_fma_f32 v[162:163], v[170:171], v[134:135], v[162:163]
	v_pk_fma_f32 v[160:161], v[172:173], v[136:137], v[160:161]
	v_pk_fma_f32 v[162:163], v[166:167], v[138:139], v[162:163]
	v_pk_fma_f32 v[164:165], v[168:169], v[140:141], v[160:161]
	v_pk_fma_f32 v[138:139], v[152:153], v[176:177], v[180:181]
	v_pk_fma_f32 v[140:141], v[150:151], v[174:175], v[178:179]
	v_pk_fma_f32 v[160:161], v[156:157], v[172:173], v[138:139]
	v_pk_fma_f32 v[138:139], v[154:155], v[170:171], v[140:141]
	v_pk_fma_f32 v[140:141], v[168:169], v[136:137], v[160:161]
	v_pk_fma_f32 v[138:139], v[166:167], v[134:135], v[138:139]
	v_pk_fma_f32 v[134:135], v[132:133], v[176:177], v[180:181]
	v_pk_fma_f32 v[136:137], v[130:131], v[174:175], v[178:179]
	v_pk_fma_f32 v[128:129], v[128:129], v[176:177], v[180:181]
	v_pk_fma_f32 v[126:127], v[126:127], v[174:175], v[178:179]
	v_pk_fma_f32 v[134:135], v[152:153], v[172:173], v[134:135]
	v_pk_fma_f32 v[160:161], v[150:151], v[170:171], v[136:137]
	v_pk_fma_f32 v[128:129], v[132:133], v[172:173], v[128:129]
	v_pk_fma_f32 v[126:127], v[130:131], v[170:171], v[126:127]
	v_pk_fma_f32 v[136:137], v[156:157], v[168:169], v[134:135]
	v_pk_fma_f32 v[134:135], v[154:155], v[166:167], v[160:161]
	v_pk_fma_f32 v[128:129], v[152:153], v[168:169], v[128:129]
	v_pk_fma_f32 v[126:127], v[150:151], v[166:167], v[126:127]
	s_nop 0
	ds_read_b128 v[130:133], v220 offset:528
	ds_read_b128 v[150:153], v220 offset:1552
	ds_read_b128 v[154:157], v220 offset:2576
	ds_read_b128 v[166:169], v220 offset:3600
	s_and_b64 vcc, exec, s[12:13]
	s_cbranch_vccnz .Lzd_3
	ds_read_b128 v[158:161], v218
	ds_read_b128 v[170:173], v217
.LBB0_1343:
	s_waitcnt lgkmcnt(0)
	s_nop 0
	v_mov_b32_dpp v170, v118 row_shr:1 row_mask:0xf bank_mask:0xf
	v_mov_b32_dpp v171, v119 row_shr:1 row_mask:0xf bank_mask:0xf
	v_mov_b32_dpp v172, v120 row_shr:1 row_mask:0xf bank_mask:0xf
	v_mov_b32_dpp v173, v121 row_shr:1 row_mask:0xf bank_mask:0xf
	v_pk_fma_f32 v[176:177], v[104:105], v[156:157], v[168:169]
	v_pk_fma_f32 v[178:179], v[102:103], v[154:155], v[166:167]
	v_mov_b32_dpp v158, v122 row_shr:1 row_mask:0xf bank_mask:0xf
	v_mov_b32_dpp v159, v123 row_shr:1 row_mask:0xf bank_mask:0xf
	v_mov_b32_dpp v160, v124 row_shr:1 row_mask:0xf bank_mask:0xf
	v_mov_b32_dpp v161, v125 row_shr:1 row_mask:0xf bank_mask:0xf
	v_pk_fma_f32 v[178:179], v[150:151], v[170:171], v[178:179]
	v_pk_fma_f32 v[176:177], v[152:153], v[172:173], v[176:177]
	v_pk_fma_f32 v[158:159], v[130:131], v[158:159], v[178:179]
	v_pk_fma_f32 v[160:161], v[132:133], v[160:161], v[176:177]
	v_pk_fma_f32 v[176:177], v[100:101], v[156:157], v[168:169]
	v_pk_fma_f32 v[178:179], v[98:99], v[154:155], v[166:167]
	v_pk_fma_f32 v[176:177], v[104:105], v[152:153], v[176:177]
	v_pk_fma_f32 v[178:179], v[102:103], v[150:151], v[178:179]
	v_pk_fma_f32 v[172:173], v[132:133], v[172:173], v[176:177]
	v_pk_fma_f32 v[170:171], v[130:131], v[170:171], v[178:179]
	v_pk_fma_f32 v[176:177], v[124:125], v[156:157], v[168:169]
	v_pk_fma_f32 v[178:179], v[122:123], v[154:155], v[166:167]
	v_pk_fma_f32 v[120:121], v[120:121], v[156:157], v[168:169]
	v_pk_fma_f32 v[118:119], v[118:119], v[154:155], v[166:167]
	v_pk_fma_f32 v[176:177], v[100:101], v[152:153], v[176:177]
	v_pk_fma_f32 v[178:179], v[98:99], v[150:151], v[178:179]
	v_pk_fma_f32 v[120:121], v[124:125], v[152:153], v[120:121]
	v_pk_fma_f32 v[118:119], v[122:123], v[150:151], v[118:119]
	v_lshl_add_u32 v174, s94, 8, v207
	v_pk_fma_f32 v[104:105], v[104:105], v[132:133], v[176:177]
	v_pk_fma_f32 v[102:103], v[102:103], v[130:131], v[178:179]
	v_pk_fma_f32 v[100:101], v[100:101], v[132:133], v[120:121]
	v_pk_fma_f32 v[98:99], v[98:99], v[130:131], v[118:119]
	s_nop 0
	v_pk_mul_f32 v[118:119], v[116:117], s[42:43] op_sel_hi:[1,0]
	v_pk_mul_f32 v[120:121], v[114:115], s[42:43] op_sel_hi:[1,0]
	v_exp_f32_e32 v118, v118
	v_exp_f32_e32 v120, v120
	v_exp_f32_e32 v119, v119
	v_exp_f32_e32 v121, v121
	v_pk_mul_f32 v[122:123], v[148:149], s[42:43] op_sel_hi:[1,0]
	v_pk_mul_f32 v[124:125], v[146:147], s[42:43] op_sel_hi:[1,0]
	v_pk_add_f32 v[118:119], v[118:119], 1.0 op_sel_hi:[1,0]
	v_pk_add_f32 v[120:121], v[120:121], 1.0 op_sel_hi:[1,0]
	v_rcp_f32_e32 v118, v118
	v_rcp_f32_e32 v120, v120
	v_rcp_f32_e32 v121, v121
	v_rcp_f32_e32 v119, v119
	v_exp_f32_e32 v124, v124
	v_exp_f32_e32 v122, v122
	v_exp_f32_e32 v123, v123
	v_exp_f32_e32 v125, v125
	v_pk_mul_f32 v[116:117], v[116:117], v[164:165]
	v_pk_mul_f32 v[114:115], v[114:115], v[162:163]
	v_pk_mul_f32 v[116:117], v[118:119], v[116:117]
	v_pk_mul_f32 v[114:115], v[120:121], v[114:115]
	v_pk_add_f32 v[118:119], v[122:123], 1.0 op_sel_hi:[1,0]
	v_pk_add_f32 v[120:121], v[124:125], 1.0 op_sel_hi:[1,0]
	v_rcp_f32_e32 v118, v118
	v_rcp_f32_e32 v120, v120
	v_rcp_f32_e32 v119, v119
	v_rcp_f32_e32 v121, v121
	v_pk_mul_f32 v[122:123], v[148:149], v[160:161]
	v_pk_mul_f32 v[124:125], v[146:147], v[158:159]
	v_pk_mul_f32 v[122:123], v[118:119], v[122:123]
	v_pk_mul_f32 v[120:121], v[120:121], v[124:125]
; #define PG8_LAS __attribute__((address_space(3)))
;     __device__ __forceinline__ void operator()(f32x4 (&acc)[2][2][4][2], const Unit& u, int p, int wr, int wc, int fr, int fq) const {
;     ...
;         for (int ai = 0; ai < 2; ++ai) { const int g = ai * 2 + wr;
; #pragma unroll
;             for (int bj = 0; bj < 2; ++bj)
; #pragma unroll
;                 for (int n = 0; n < 2; ++n) {
;                     const f32x4 w0 = *(const PG8_LAS f32x4*)(Tw + bj * 128 + 4 * n), w1 = *(const PG8_LAS f32x4*)(Tw + 256 + bj * 128 + 4 * n), w2 = *(const PG8_LAS f32x4*)(Tw + 512 + bj * 128 + 4 * n), bb = *(const PG8_LAS f32x4*)(Tw + 768 + bj * 128 + 4 * n);
;                     f32x4 h62 = (f32x4){0.f, 0.f, 0.f, 0.f}, h63 = h62;
;                     if (g > 0) { h62 = *(const PG8_LAS f32x4*)(X + (((g - 1) * 2 + 0) * 256) + bj * 128 + tcol + 4 * n); h63 = *(const PG8_LAS f32x4*)(X + (((g - 1) * 2 + 1) * 256) + bj * 128 + tcol + 4 * n); }
;                     const f32x4 x0 = acc[ai][bj][0][n], x1 = acc[ai][bj][1][n], x2 = acc[ai][bj][2][n], x3 = acc[ai][bj][3][n];
;                     f32x4 s2, s3;
; #pragma unroll
;                     for (int e = 0; e < 4; ++e) { s3[e] = dpp_shr_fill<1>(h63[e], x3[e]); s2[e] = dpp_shr_fill<1>(h62[e], x2[e]); }
;                     f32x4 r0 = bb + w2 * x0 + w1 * s3 + w0 * s2, r1 = bb + w2 * x1 + w1 * x0 + w0 * s3, r2 = bb + w2 * x2 + w1 * x1 + w0 * x0, r3 = bb + w2 * x3 + w1 * x2 + w0 * x1;
;                     asm volatile("" : "+v"(r0), "+v"(r1), "+v"(r2), "+v"(r3));
;                     acc[ai][bj][0][n] = r0; acc[ai][bj][1][n] = r1; acc[ai][bj][2][n] = r2; acc[ai][bj][3][n] = r3;
;                     __builtin_amdgcn_sched_barrier(0); }
; #pragma unroll
;             for (int m = 0; m < 4; ++m) { f32x4 o[2];
; #pragma unroll
;                 for (int n = 0; n < 2; ++n) { const f32x4 gt = acc[ai][0][m][n], a = gt * -1.4426950408889634f, gu = gt * acc[ai][1][m][n];
;                     f32x4 ex; ex.x = __builtin_amdgcn_exp2f(a.x); ex.y = __builtin_amdgcn_exp2f(a.y); ex.z = __builtin_amdgcn_exp2f(a.z); ex.w = __builtin_amdgcn_exp2f(a.w);
;                     const f32x4 d = ex + 1.0f; f32x4 r; r.x = __builtin_amdgcn_rcpf(d.x); r.y = __builtin_amdgcn_rcpf(d.y); r.z = __builtin_amdgcn_rcpf(d.z); r.w = __builtin_amdgcn_rcpf(d.w);
;                     o[n] = gu * r; }
	v_cvt_pk_bf16_f32 v118, v114, v115
	v_cvt_pk_bf16_f32 v119, v116, v117
	v_mov_b64_e32 v[116:117], s[76:77]
	v_cvt_pk_bf16_f32 v120, v120, v121
	v_cvt_pk_bf16_f32 v121, v122, v123
	v_mad_i64_i32 v[122:123], s[12:13], v174, s22, v[116:117]
	v_lshlrev_b64 v[114:115], 1, v[200:201]
	v_lshl_add_u64 v[122:123], v[122:123], 0, v[114:115]
	global_store_dwordx4 v[122:123], v[118:121], off
	v_pk_mul_f32 v[122:123], v[144:145], s[42:43] op_sel_hi:[1,0]
	v_pk_mul_f32 v[124:125], v[142:143], s[42:43] op_sel_hi:[1,0]
	v_pk_mul_f32 v[118:119], v[108:109], s[42:43] op_sel_hi:[1,0]
	v_pk_mul_f32 v[120:121], v[106:107], s[42:43] op_sel_hi:[1,0]
	v_exp_f32_e32 v118, v118
	v_exp_f32_e32 v119, v119
	v_exp_f32_e32 v120, v120
	v_exp_f32_e32 v121, v121
	v_exp_f32_e32 v122, v122
	v_pk_add_f32 v[118:119], v[118:119], 1.0 op_sel_hi:[1,0]
	v_exp_f32_e32 v123, v123
	v_pk_add_f32 v[120:121], v[120:121], 1.0 op_sel_hi:[1,0]
	v_rcp_f32_e32 v118, v118
	v_rcp_f32_e32 v119, v119
	v_rcp_f32_e32 v120, v120
	v_rcp_f32_e32 v121, v121
	v_exp_f32_e32 v124, v124
	v_exp_f32_e32 v125, v125
	v_pk_mul_f32 v[108:109], v[108:109], v[140:141]
	v_pk_mul_f32 v[106:107], v[106:107], v[138:139]
	v_pk_mul_f32 v[108:109], v[118:119], v[108:109]
	v_pk_add_f32 v[118:119], v[122:123], 1.0 op_sel_hi:[1,0]
	v_pk_mul_f32 v[106:107], v[120:121], v[106:107]
	v_pk_add_f32 v[120:121], v[124:125], 1.0 op_sel_hi:[1,0]
	v_rcp_f32_e32 v118, v118
	v_rcp_f32_e32 v119, v119
	v_rcp_f32_e32 v120, v120
	v_rcp_f32_e32 v121, v121
	v_pk_mul_f32 v[122:123], v[144:145], v[172:173]
	v_pk_mul_f32 v[124:125], v[142:143], v[170:171]
	v_pk_mul_f32 v[118:119], v[118:119], v[122:123]
	v_pk_mul_f32 v[120:121], v[120:121], v[124:125]
	v_cvt_pk_bf16_f32 v106, v106, v107
	v_cvt_pk_bf16_f32 v107, v108, v109
	v_pk_mul_f32 v[102:103], v[110:111], v[102:103]
	v_cvt_pk_bf16_f32 v108, v120, v121
	v_cvt_pk_bf16_f32 v109, v118, v119
	v_or_b32_e32 v118, 1, v174
	v_mad_i64_i32 v[118:119], s[12:13], v118, s22, v[116:117]
	v_lshl_add_u64 v[118:119], v[118:119], 0, v[114:115]
	global_store_dwordx4 v[118:119], v[106:109], off
	v_pk_mul_f32 v[120:121], v[110:111], s[42:43] op_sel_hi:[1,0]
	v_pk_mul_f32 v[118:119], v[112:113], s[42:43] op_sel_hi:[1,0]
	v_pk_mul_f32 v[108:109], v[90:91], s[42:43] op_sel_hi:[1,0]
	v_pk_mul_f32 v[106:107], v[92:93], s[42:43] op_sel_hi:[1,0]
	v_exp_f32_e32 v108, v108
	v_exp_f32_e32 v109, v109
	v_exp_f32_e32 v106, v106
	v_exp_f32_e32 v107, v107
	v_exp_f32_e32 v120, v120
	v_pk_add_f32 v[108:109], v[108:109], 1.0 op_sel_hi:[1,0]
	v_exp_f32_e32 v121, v121
	v_rcp_f32_e32 v108, v108
	v_rcp_f32_e32 v109, v109
	v_pk_mul_f32 v[90:91], v[90:91], v[134:135]
	v_pk_add_f32 v[106:107], v[106:107], 1.0 op_sel_hi:[1,0]
	v_exp_f32_e32 v118, v118
	v_rcp_f32_e32 v106, v106
	v_rcp_f32_e32 v107, v107
	v_exp_f32_e32 v119, v119
	v_pk_mul_f32 v[90:91], v[108:109], v[90:91]
	v_pk_add_f32 v[108:109], v[120:121], 1.0 op_sel_hi:[1,0]
	v_pk_mul_f32 v[92:93], v[92:93], v[136:137]
	v_rcp_f32_e32 v108, v108
	v_rcp_f32_e32 v109, v109
	v_pk_mul_f32 v[92:93], v[106:107], v[92:93]
	v_pk_add_f32 v[106:107], v[118:119], 1.0 op_sel_hi:[1,0]
	v_cvt_pk_bf16_f32 v90, v90, v91
	v_pk_mul_f32 v[102:103], v[108:109], v[102:103]
	v_rcp_f32_e32 v106, v106
	v_rcp_f32_e32 v107, v107
	v_cvt_pk_bf16_f32 v91, v92, v93
	v_cvt_pk_bf16_f32 v92, v102, v103
	v_or_b32_e32 v102, 2, v174
	v_mad_i64_i32 v[102:103], s[12:13], v102, s22, v[116:117]
	v_pk_mul_f32 v[104:105], v[112:113], v[104:105]
	v_lshl_add_u64 v[102:103], v[102:103], 0, v[114:115]
	v_pk_mul_f32 v[104:105], v[106:107], v[104:105]
	s_nop 0
	v_cvt_pk_bf16_f32 v93, v104, v105
	global_store_dwordx4 v[102:103], v[90:93], off
	v_pk_mul_f32 v[102:103], v[96:97], s[42:43] op_sel_hi:[1,0]
	v_pk_mul_f32 v[104:105], v[94:95], s[42:43] op_sel_hi:[1,0]
	v_pk_mul_f32 v[90:91], v[88:89], s[42:43] op_sel_hi:[1,0]
	v_pk_mul_f32 v[92:93], v[86:87], s[42:43] op_sel_hi:[1,0]
	v_exp_f32_e32 v90, v90
	v_exp_f32_e32 v91, v91
	v_exp_f32_e32 v92, v92
	v_exp_f32_e32 v93, v93
	v_exp_f32_e32 v102, v102
	v_pk_add_f32 v[90:91], v[90:91], 1.0 op_sel_hi:[1,0]
	v_exp_f32_e32 v103, v103
	v_pk_add_f32 v[92:93], v[92:93], 1.0 op_sel_hi:[1,0]
	v_rcp_f32_e32 v90, v90
	v_rcp_f32_e32 v91, v91
	v_rcp_f32_e32 v92, v92
	v_rcp_f32_e32 v93, v93
	v_exp_f32_e32 v104, v104
	v_exp_f32_e32 v105, v105
	v_pk_mul_f32 v[88:89], v[88:89], v[128:129]
	v_pk_mul_f32 v[86:87], v[86:87], v[126:127]
	v_pk_mul_f32 v[88:89], v[90:91], v[88:89]
	v_pk_add_f32 v[90:91], v[102:103], 1.0 op_sel_hi:[1,0]
	v_pk_mul_f32 v[86:87], v[92:93], v[86:87]
	v_pk_add_f32 v[92:93], v[104:105], 1.0 op_sel_hi:[1,0]
	v_rcp_f32_e32 v90, v90
	v_rcp_f32_e32 v91, v91
	v_rcp_f32_e32 v92, v92
	v_rcp_f32_e32 v93, v93
	v_pk_mul_f32 v[96:97], v[96:97], v[100:101]
	v_pk_mul_f32 v[94:95], v[94:95], v[98:99]
	v_pk_mul_f32 v[90:91], v[90:91], v[96:97]
	v_pk_mul_f32 v[92:93], v[92:93], v[94:95]
	v_cvt_pk_bf16_f32 v86, v86, v87
	v_cvt_pk_bf16_f32 v87, v88, v89
	s_nop 0
	v_cvt_pk_bf16_f32 v88, v92, v93
	v_cvt_pk_bf16_f32 v89, v90, v91
	v_or_b32_e32 v90, 3, v174
	v_mad_i64_i32 v[90:91], s[12:13], v90, s22, v[116:117]
	v_lshl_add_u64 v[90:91], v[90:91], 0, v[114:115]
	global_store_dwordx4 v[90:91], v[86:89], off
	ds_read_b128 v[88:91], v220
	ds_read_b128 v[92:95], v220 offset:1024
	ds_read_b128 v[96:99], v220 offset:2048
	ds_read_b128 v[100:103], v220 offset:3072
	v_cndmask_b32_e64 v87, 0, 1, s[82:83]
	v_cmp_ne_u32_e64 s[12:13], 1, v87
	s_andn2_b64 vcc, exec, s[82:83]
	s_cbranch_vccnz .Lzd_4
	ds_read_b128 v[108:111], v210 offset:2048
	ds_read_b128 v[104:107], v210 offset:3072
; #define PG8_LAS __attribute__((address_space(3)))
; template <int SH> __device__ __forceinline__ float dpp_shr_fill(float fill, float cur) { return i2f(__builtin_amdgcn_update_dpp(f2i(fill), f2i(cur), 0x110 + SH, 0xf, 0xf, false)); }
;     template <bool PR = false> __device__ __forceinline__ void apply(f32x4 (&acc)[2][2][4][2], int p, int wr, int wc, int fr, int fq) const {
;     ...
;             for (int m = 0; m < 4; ++m) rs[ai][m] = __builtin_amdgcn_rsqf((float)Tr[ai * HALF + (PR ? m : m * 16)] * (1.0f / (1048576.0f * 2048.0f)) + 1e-6f);
; #pragma unroll
;         for (int bj = 0; bj < 2; ++bj)
; #pragma unroll
;             for (int n = 0; n < 2; ++n) { const f32x4 bv = *(const PG8_LAS f32x4*)(Tb + bj * HALF + 4 * n);
; #pragma unroll
;                 for (int ai = 0; ai < 2; ++ai)
; #pragma unroll
;                     for (int m = 0; m < 4; ++m) acc[ai][bj][m][n] = acc[ai][bj][m][n] * rs[ai][m] + bv; }
;     __device__ __forceinline__ void operator()(f32x4 (&acc)[2][2][4][2], const Unit& u, int p, int wr, int wc, int fr, int fq) const {
;     ...
;                     const f32x4 w0 = *(const PG8_LAS f32x4*)(Tw + bj * 128 + 4 * n), w1 = *(const PG8_LAS f32x4*)(Tw + 256 + bj * 128 + 4 * n), w2 = *(const PG8_LAS f32x4*)(Tw + 512 + bj * 128 + 4 * n), bb = *(const PG8_LAS f32x4*)(Tw + 768 + bj * 128 + 4 * n);
;                     f32x4 h62 = (f32x4){0.f, 0.f, 0.f, 0.f}, h63 = h62;
;                     if (g > 0) { h62 = *(const PG8_LAS f32x4*)(X + (((g - 1) * 2 + 0) * 256) + bj * 128 + tcol + 4 * n); h63 = *(const PG8_LAS f32x4*)(X + (((g - 1) * 2 + 1) * 256) + bj * 128 + tcol + 4 * n); }
;                     const f32x4 x0 = acc[ai][bj][0][n], x1 = acc[ai][bj][1][n], x2 = acc[ai][bj][2][n], x3 = acc[ai][bj][3][n];
;                     f32x4 s2, s3;
; #pragma unroll
;                     for (int e = 0; e < 4; ++e) { s3[e] = dpp_shr_fill<1>(h63[e], x3[e]); s2[e] = dpp_shr_fill<1>(h62[e], x2[e]); }
;                     f32x4 r0 = bb + w2 * x0 + w1 * s3 + w0 * s2, r1 = bb + w2 * x1 + w1 * x0 + w0 * s3, r2 = bb + w2 * x2 + w1 * x1 + w0 * x0, r3 = bb + w2 * x3 + w1 * x2 + w0 * x1;
;                     asm volatile("" : "+v"(r0), "+v"(r1), "+v"(r2), "+v"(r3));
;                     acc[ai][bj][0][n] = r0; acc[ai][bj][1][n] = r1; acc[ai][bj][2][n] = r2; acc[ai][bj][3][n] = r3;
.LBB0_1345:
	v_ffbh_u32_e32 v87, v71
	v_min_u32_e32 v87, 32, v87
	v_lshlrev_b64 v[70:71], v87, v[70:71]
	v_min_u32_e32 v70, 1, v70
	v_or_b32_e32 v70, v71, v70
	v_cvt_f32_u32_e32 v70, v70
	v_ffbh_u32_e32 v71, v73
	v_min_u32_e32 v112, 32, v71
	v_sub_u32_e32 v71, 32, v87
	v_ldexp_f32 v87, v70, v71
	v_lshlrev_b64 v[70:71], v112, v[72:73]
	v_min_u32_e32 v70, 1, v70
	v_or_b32_e32 v70, v71, v70
	v_cvt_f32_u32_e32 v70, v70
	v_fmamk_f32 v71, v87, 0x30000000, v233
	v_rsq_f32_e32 v116, v71
	v_sub_u32_e32 v71, 32, v112
	v_ldexp_f32 v70, v70, v71
	v_fmamk_f32 v70, v70, 0x30000000, v233
	v_rsq_f32_e32 v112, v70
	v_pk_fma_f32 v[30:31], v[30:31], v[116:117], v[82:83] op_sel_hi:[1,0,1]
	v_pk_fma_f32 v[32:33], v[32:33], v[116:117], v[84:85] op_sel_hi:[1,0,1]
	s_waitcnt lgkmcnt(0)
	v_mov_b32_dpp v104, v78 row_shr:1 row_mask:0xf bank_mask:0xf
	v_mov_b32_dpp v105, v79 row_shr:1 row_mask:0xf bank_mask:0xf
	v_mov_b32_dpp v106, v80 row_shr:1 row_mask:0xf bank_mask:0xf
	v_mov_b32_dpp v107, v81 row_shr:1 row_mask:0xf bank_mask:0xf
	v_pk_fma_f32 v[70:71], v[32:33], v[98:99], v[102:103]
	v_pk_fma_f32 v[72:73], v[30:31], v[96:97], v[100:101]
	v_pk_fma_f32 v[26:27], v[26:27], v[112:113], v[82:83] op_sel_hi:[1,0,1]
	v_pk_fma_f32 v[28:29], v[28:29], v[112:113], v[84:85] op_sel_hi:[1,0,1]
	v_mov_b32_dpp v108, v74 row_shr:1 row_mask:0xf bank_mask:0xf
	v_mov_b32_dpp v109, v75 row_shr:1 row_mask:0xf bank_mask:0xf
	v_mov_b32_dpp v110, v76 row_shr:1 row_mask:0xf bank_mask:0xf
	v_mov_b32_dpp v111, v77 row_shr:1 row_mask:0xf bank_mask:0xf
	v_pk_fma_f32 v[72:73], v[92:93], v[104:105], v[72:73]
	v_pk_fma_f32 v[70:71], v[94:95], v[106:107], v[70:71]
	v_pk_fma_f32 v[82:83], v[88:89], v[108:109], v[72:73]
	v_pk_fma_f32 v[84:85], v[90:91], v[110:111], v[70:71]
	v_pk_fma_f32 v[70:71], v[28:29], v[98:99], v[102:103]
	v_pk_fma_f32 v[72:73], v[26:27], v[96:97], v[100:101]
	v_pk_fma_f32 v[70:71], v[32:33], v[94:95], v[70:71]
	v_pk_fma_f32 v[108:109], v[30:31], v[92:93], v[72:73]
	v_pk_fma_f32 v[72:73], v[90:91], v[106:107], v[70:71]
	v_pk_fma_f32 v[70:71], v[88:89], v[104:105], v[108:109]
	v_pk_fma_f32 v[104:105], v[76:77], v[98:99], v[102:103]
	v_pk_fma_f32 v[106:107], v[74:75], v[96:97], v[100:101]
	v_pk_fma_f32 v[80:81], v[80:81], v[98:99], v[102:103]
	v_pk_fma_f32 v[78:79], v[78:79], v[96:97], v[100:101]
	v_pk_fma_f32 v[104:105], v[28:29], v[94:95], v[104:105]
	v_pk_fma_f32 v[106:107], v[26:27], v[92:93], v[106:107]
	v_pk_fma_f32 v[76:77], v[76:77], v[94:95], v[80:81]
	v_pk_fma_f32 v[74:75], v[74:75], v[92:93], v[78:79]
	v_pk_fma_f32 v[32:33], v[32:33], v[90:91], v[104:105]
	v_pk_fma_f32 v[30:31], v[30:31], v[88:89], v[106:107]
	v_pk_fma_f32 v[28:29], v[28:29], v[90:91], v[76:77]
	v_pk_fma_f32 v[26:27], v[26:27], v[88:89], v[74:75]
	s_nop 0
	ds_read_b128 v[78:81], v220 offset:16
	ds_read_b128 v[90:93], v220 offset:1040
	ds_read_b128 v[94:97], v220 offset:2064
	ds_read_b128 v[98:101], v220 offset:3088
	s_and_b64 vcc, exec, s[12:13]
	s_cbranch_vccnz .Lzd_5
	ds_read_b128 v[86:89], v210 offset:2064
	ds_read_b128 v[102:105], v210 offset:3088
; #define PG8_LAS __attribute__((address_space(3)))
; template <int SH> __device__ __forceinline__ float dpp_shr_fill(float fill, float cur) { return i2f(__builtin_amdgcn_update_dpp(f2i(fill), f2i(cur), 0x110 + SH, 0xf, 0xf, false)); }
;     template <bool PR = false> __device__ __forceinline__ void apply(f32x4 (&acc)[2][2][4][2], int p, int wr, int wc, int fr, int fq) const {
;     ...
;             for (int m = 0; m < 4; ++m) rs[ai][m] = __builtin_amdgcn_rsqf((float)Tr[ai * HALF + (PR ? m : m * 16)] * (1.0f / (1048576.0f * 2048.0f)) + 1e-6f);
; #pragma unroll
;         for (int bj = 0; bj < 2; ++bj)
; #pragma unroll
;             for (int n = 0; n < 2; ++n) { const f32x4 bv = *(const PG8_LAS f32x4*)(Tb + bj * HALF + 4 * n);
; #pragma unroll
;                 for (int ai = 0; ai < 2; ++ai)
; #pragma unroll
;                     for (int m = 0; m < 4; ++m) acc[ai][bj][m][n] = acc[ai][bj][m][n] * rs[ai][m] + bv; }
;     __device__ __forceinline__ void operator()(f32x4 (&acc)[2][2][4][2], const Unit& u, int p, int wr, int wc, int fr, int fq) const {
;     ...
;                     const f32x4 w0 = *(const PG8_LAS f32x4*)(Tw + bj * 128 + 4 * n), w1 = *(const PG8_LAS f32x4*)(Tw + 256 + bj * 128 + 4 * n), w2 = *(const PG8_LAS f32x4*)(Tw + 512 + bj * 128 + 4 * n), bb = *(const PG8_LAS f32x4*)(Tw + 768 + bj * 128 + 4 * n);
;                     f32x4 h62 = (f32x4){0.f, 0.f, 0.f, 0.f}, h63 = h62;
;                     if (g > 0) { h62 = *(const PG8_LAS f32x4*)(X + (((g - 1) * 2 + 0) * 256) + bj * 128 + tcol + 4 * n); h63 = *(const PG8_LAS f32x4*)(X + (((g - 1) * 2 + 1) * 256) + bj * 128 + tcol + 4 * n); }
;                     const f32x4 x0 = acc[ai][bj][0][n], x1 = acc[ai][bj][1][n], x2 = acc[ai][bj][2][n], x3 = acc[ai][bj][3][n];
;                     f32x4 s2, s3;
; #pragma unroll
;                     for (int e = 0; e < 4; ++e) { s3[e] = dpp_shr_fill<1>(h63[e], x3[e]); s2[e] = dpp_shr_fill<1>(h62[e], x2[e]); }
;                     f32x4 r0 = bb + w2 * x0 + w1 * s3 + w0 * s2, r1 = bb + w2 * x1 + w1 * x0 + w0 * s3, r2 = bb + w2 * x2 + w1 * x1 + w0 * x0, r3 = bb + w2 * x3 + w1 * x2 + w0 * x1;
;                     asm volatile("" : "+v"(r0), "+v"(r1), "+v"(r2), "+v"(r3));
;                     acc[ai][bj][0][n] = r0; acc[ai][bj][1][n] = r1; acc[ai][bj][2][n] = r2; acc[ai][bj][3][n] = r3;
.LBB0_1347:
	v_mov_b32_e32 v117, v116
	v_mov_b32_e32 v106, v116
	v_mov_b32_e32 v107, v116
	v_mov_b32_e32 v113, v112
	v_pk_fma_f32 v[24:25], v[24:25], v[106:107], v[68:69]
	v_pk_fma_f32 v[22:23], v[22:23], v[116:117], v[66:67]
	v_mov_b32_e32 v108, v112
	v_mov_b32_e32 v109, v112
	v_pk_fma_f32 v[20:21], v[20:21], v[108:109], v[68:69]
	v_pk_fma_f32 v[18:19], v[18:19], v[112:113], v[66:67]
	s_waitcnt lgkmcnt(0)
	v_mov_b32_dpp v102, v62 row_shr:1 row_mask:0xf bank_mask:0xf
	v_mov_b32_dpp v103, v63 row_shr:1 row_mask:0xf bank_mask:0xf
	v_mov_b32_dpp v104, v64 row_shr:1 row_mask:0xf bank_mask:0xf
	v_mov_b32_dpp v105, v65 row_shr:1 row_mask:0xf bank_mask:0xf
	v_pk_fma_f32 v[66:67], v[24:25], v[96:97], v[100:101]
	v_pk_fma_f32 v[68:69], v[22:23], v[94:95], v[98:99]
	v_mov_b32_dpp v86, v58 row_shr:1 row_mask:0xf bank_mask:0xf
	v_mov_b32_dpp v87, v59 row_shr:1 row_mask:0xf bank_mask:0xf
	v_mov_b32_dpp v88, v60 row_shr:1 row_mask:0xf bank_mask:0xf
	v_mov_b32_dpp v89, v61 row_shr:1 row_mask:0xf bank_mask:0xf
	v_pk_fma_f32 v[66:67], v[92:93], v[104:105], v[66:67]
	v_pk_fma_f32 v[68:69], v[90:91], v[102:103], v[68:69]
	v_pk_fma_f32 v[76:77], v[80:81], v[88:89], v[66:67]
	v_pk_fma_f32 v[74:75], v[78:79], v[86:87], v[68:69]
	v_pk_fma_f32 v[66:67], v[20:21], v[96:97], v[100:101]
	v_pk_fma_f32 v[68:69], v[18:19], v[94:95], v[98:99]
	v_pk_fma_f32 v[66:67], v[24:25], v[92:93], v[66:67]
	v_pk_fma_f32 v[86:87], v[22:23], v[90:91], v[68:69]
	v_pk_fma_f32 v[68:69], v[80:81], v[104:105], v[66:67]
	v_pk_fma_f32 v[66:67], v[78:79], v[102:103], v[86:87]
	v_pk_fma_f32 v[86:87], v[60:61], v[96:97], v[100:101]
	v_pk_fma_f32 v[88:89], v[58:59], v[94:95], v[98:99]
	v_pk_fma_f32 v[64:65], v[64:65], v[96:97], v[100:101]
	v_pk_fma_f32 v[62:63], v[62:63], v[94:95], v[98:99]
	v_pk_fma_f32 v[86:87], v[20:21], v[92:93], v[86:87]
	v_pk_fma_f32 v[88:89], v[18:19], v[90:91], v[88:89]
	v_pk_fma_f32 v[60:61], v[60:61], v[92:93], v[64:65]
	v_pk_fma_f32 v[58:59], v[58:59], v[90:91], v[62:63]
	v_pk_fma_f32 v[24:25], v[24:25], v[80:81], v[86:87]
	v_pk_fma_f32 v[22:23], v[22:23], v[78:79], v[88:89]
	v_pk_fma_f32 v[20:21], v[20:21], v[80:81], v[60:61]
	v_pk_fma_f32 v[18:19], v[18:19], v[78:79], v[58:59]
	s_nop 0
	ds_read_b128 v[78:81], v220 offset:512
	ds_read_b128 v[86:89], v220 offset:1536
	ds_read_b128 v[90:93], v220 offset:2560
	ds_read_b128 v[94:97], v220 offset:3584
	s_and_b64 vcc, exec, s[12:13]
	s_cbranch_vccnz .Lzd_6
	ds_read_b128 v[62:65], v210 offset:2560
	ds_read_b128 v[98:101], v210 offset:3584
.LBB0_1349:
	v_pk_fma_f32 v[16:17], v[16:17], v[106:107], v[56:57]
	v_pk_fma_f32 v[14:15], v[14:15], v[116:117], v[54:55]
	v_pk_fma_f32 v[12:13], v[12:13], v[108:109], v[56:57]
	v_pk_fma_f32 v[10:11], v[10:11], v[112:113], v[54:55]
	s_waitcnt lgkmcnt(0)
	v_mov_b32_dpp v98, v50 row_shr:1 row_mask:0xf bank_mask:0xf
	v_mov_b32_dpp v99, v51 row_shr:1 row_mask:0xf bank_mask:0xf
	v_mov_b32_dpp v100, v52 row_shr:1 row_mask:0xf bank_mask:0xf
	v_mov_b32_dpp v101, v53 row_shr:1 row_mask:0xf bank_mask:0xf
	v_pk_fma_f32 v[54:55], v[16:17], v[92:93], v[96:97]
	v_pk_fma_f32 v[56:57], v[14:15], v[90:91], v[94:95]
	v_mov_b32_dpp v62, v46 row_shr:1 row_mask:0xf bank_mask:0xf
	v_mov_b32_dpp v63, v47 row_shr:1 row_mask:0xf bank_mask:0xf
	v_mov_b32_dpp v64, v48 row_shr:1 row_mask:0xf bank_mask:0xf
	v_mov_b32_dpp v65, v49 row_shr:1 row_mask:0xf bank_mask:0xf
	v_pk_fma_f32 v[54:55], v[88:89], v[100:101], v[54:55]
	v_pk_fma_f32 v[56:57], v[86:87], v[98:99], v[56:57]
	v_pk_fma_f32 v[64:65], v[80:81], v[64:65], v[54:55]
	v_pk_fma_f32 v[62:63], v[78:79], v[62:63], v[56:57]
	v_pk_fma_f32 v[54:55], v[12:13], v[92:93], v[96:97]
	v_pk_fma_f32 v[56:57], v[10:11], v[90:91], v[94:95]
	v_pk_fma_f32 v[54:55], v[16:17], v[88:89], v[54:55]
	v_pk_fma_f32 v[60:61], v[14:15], v[86:87], v[56:57]
	v_pk_fma_f32 v[56:57], v[80:81], v[100:101], v[54:55]
	v_pk_fma_f32 v[54:55], v[78:79], v[98:99], v[60:61]
	v_pk_fma_f32 v[60:61], v[48:49], v[92:93], v[96:97]
	v_pk_fma_f32 v[98:99], v[46:47], v[90:91], v[94:95]
	v_pk_fma_f32 v[52:53], v[52:53], v[92:93], v[96:97]
	v_pk_fma_f32 v[50:51], v[50:51], v[90:91], v[94:95]
	v_pk_fma_f32 v[60:61], v[12:13], v[88:89], v[60:61]
	v_pk_fma_f32 v[98:99], v[10:11], v[86:87], v[98:99]
	v_pk_fma_f32 v[48:49], v[48:49], v[88:89], v[52:53]
	v_pk_fma_f32 v[46:47], v[46:47], v[86:87], v[50:51]
	v_pk_fma_f32 v[16:17], v[16:17], v[80:81], v[60:61]
	v_pk_fma_f32 v[14:15], v[14:15], v[78:79], v[98:99]
	v_pk_fma_f32 v[12:13], v[12:13], v[80:81], v[48:49]
	v_pk_fma_f32 v[10:11], v[10:11], v[78:79], v[46:47]
	s_nop 0
	ds_read_b128 v[46:49], v220 offset:528
	ds_read_b128 v[50:53], v220 offset:1552
	ds_read_b128 v[78:81], v220 offset:2576
	ds_read_b128 v[86:89], v220 offset:3600
	s_and_b64 vcc, exec, s[12:13]
	s_cbranch_vccnz .Lzd_7
	ds_read_b128 v[58:61], v210 offset:2576
	ds_read_b128 v[90:93], v210 offset:3600
